# pool_item (latent) 64x64x64 f32 matmul moved from packed-f32 VALU FMAs to v_mfma_f32_32x32x2_f32, one 32x32 tile per wave
# speedup vs baseline: 1.0269x; 1.0080x over previous
; DI void pool_item(const Params& p, int layer, int seq, int tile, int g, char* smem) {
;     ...
;     float acc[16];
; #pragma unroll
;     for (int i = 0; i < 16; ++i) acc[i] = 0.f;
; #pragma unroll 1
;     for (int c4 = 0; c4 < 16; ++c4) {
;         const float w0 = sw[(4 * c4) * 64 + e], w1 = sw[(4 * c4 + 1) * 64 + e], w2_ = sw[(4 * c4 + 2) * 64 + e], w3 = sw[(4 * c4 + 3) * 64 + e];
; #pragma unroll
;         for (int i = 0; i < 16; ++i) { const float4 d = *(const float4*)(sd + (tq * 16 + i) * 68 + 4 * c4); acc[i] += d.x * w0 + d.y * w1 + d.z * w2_ + d.w * w3; }
;     }
.LBB0_304:
	v_and_b32_e32 v47, 31, v30
	v_lshrrev_b32_e32 v48, 5, v30
	v_bfe_u32 v43, v3, 5, 1
	v_bfe_u32 v46, v3, 4, 1
	v_lshl_add_u32 v40, v43, 5, v47
	v_mul_u32_u24_e32 v40, 0x110, v40
	v_lshl_add_u32 v40, v48, 2, v40
	v_add_u32_e32 v40, s16, v40
	v_lshl_add_u32 v44, v46, 5, v47
	v_lshlrev_b32_e32 v41, 8, v48
	v_lshl_add_u32 v41, v44, 2, v41
	v_add_u32_e32 v41, s17, v41
	v_lshlrev_b32_e32 v42, 5, v43
	v_lshl_add_u32 v42, v48, 2, v42
	v_lshlrev_b32_e32 v42, 11, v42
	v_lshl_add_u32 v42, v44, 1, v42
	s_waitcnt lgkmcnt(0)
	s_barrier
	ds_read_b32 v50, v40
	ds_read_b32 v51, v41
	ds_read_b32 v52, v40 offset:8
	ds_read_b32 v53, v41 offset:512
	ds_read_b32 v54, v40 offset:16
	ds_read_b32 v55, v41 offset:1024
	ds_read_b32 v56, v40 offset:24
	ds_read_b32 v57, v41 offset:1536
	s_waitcnt lgkmcnt(6)
	v_mfma_f32_32x32x2_f32 v[0:15], v50, v51, 0
	ds_read_b32 v50, v40 offset:32
	ds_read_b32 v51, v41 offset:2048
	s_waitcnt lgkmcnt(6)
	v_mfma_f32_32x32x2_f32 v[0:15], v52, v53, v[0:15]
	ds_read_b32 v52, v40 offset:40
	ds_read_b32 v53, v41 offset:2560
	s_waitcnt lgkmcnt(6)
	v_mfma_f32_32x32x2_f32 v[0:15], v54, v55, v[0:15]
	ds_read_b32 v54, v40 offset:48
	ds_read_b32 v55, v41 offset:3072
	s_waitcnt lgkmcnt(6)
	v_mfma_f32_32x32x2_f32 v[0:15], v56, v57, v[0:15]
	ds_read_b32 v56, v40 offset:56
	ds_read_b32 v57, v41 offset:3584
	s_waitcnt lgkmcnt(6)
	v_mfma_f32_32x32x2_f32 v[0:15], v50, v51, v[0:15]
	ds_read_b32 v50, v40 offset:64
	ds_read_b32 v51, v41 offset:4096
	s_waitcnt lgkmcnt(6)
	v_mfma_f32_32x32x2_f32 v[0:15], v52, v53, v[0:15]
	ds_read_b32 v52, v40 offset:72
	ds_read_b32 v53, v41 offset:4608
	s_waitcnt lgkmcnt(6)
	v_mfma_f32_32x32x2_f32 v[0:15], v54, v55, v[0:15]
	ds_read_b32 v54, v40 offset:80
	ds_read_b32 v55, v41 offset:5120
	s_waitcnt lgkmcnt(6)
	v_mfma_f32_32x32x2_f32 v[0:15], v56, v57, v[0:15]
	ds_read_b32 v56, v40 offset:88
	ds_read_b32 v57, v41 offset:5632
	s_waitcnt lgkmcnt(6)
	v_mfma_f32_32x32x2_f32 v[0:15], v50, v51, v[0:15]
	ds_read_b32 v50, v40 offset:96
	ds_read_b32 v51, v41 offset:6144
	s_waitcnt lgkmcnt(6)
	v_mfma_f32_32x32x2_f32 v[0:15], v52, v53, v[0:15]
	ds_read_b32 v52, v40 offset:104
	ds_read_b32 v53, v41 offset:6656
	s_waitcnt lgkmcnt(6)
	v_mfma_f32_32x32x2_f32 v[0:15], v54, v55, v[0:15]
	ds_read_b32 v54, v40 offset:112
	ds_read_b32 v55, v41 offset:7168
	s_waitcnt lgkmcnt(6)
	v_mfma_f32_32x32x2_f32 v[0:15], v56, v57, v[0:15]
	ds_read_b32 v56, v40 offset:120
	ds_read_b32 v57, v41 offset:7680
	s_waitcnt lgkmcnt(6)
	v_mfma_f32_32x32x2_f32 v[0:15], v50, v51, v[0:15]
	ds_read_b32 v50, v40 offset:128
	ds_read_b32 v51, v41 offset:8192
	s_waitcnt lgkmcnt(6)
	v_mfma_f32_32x32x2_f32 v[0:15], v52, v53, v[0:15]
	ds_read_b32 v52, v40 offset:136
	ds_read_b32 v53, v41 offset:8704
	s_waitcnt lgkmcnt(6)
	v_mfma_f32_32x32x2_f32 v[0:15], v54, v55, v[0:15]
	ds_read_b32 v54, v40 offset:144
	ds_read_b32 v55, v41 offset:9216
	s_waitcnt lgkmcnt(6)
	v_mfma_f32_32x32x2_f32 v[0:15], v56, v57, v[0:15]
	ds_read_b32 v56, v40 offset:152
	ds_read_b32 v57, v41 offset:9728
	s_waitcnt lgkmcnt(6)
	v_mfma_f32_32x32x2_f32 v[0:15], v50, v51, v[0:15]
	ds_read_b32 v50, v40 offset:160
	ds_read_b32 v51, v41 offset:10240
	s_waitcnt lgkmcnt(6)
	v_mfma_f32_32x32x2_f32 v[0:15], v52, v53, v[0:15]
	ds_read_b32 v52, v40 offset:168
	ds_read_b32 v53, v41 offset:10752
	s_waitcnt lgkmcnt(6)
	v_mfma_f32_32x32x2_f32 v[0:15], v54, v55, v[0:15]
	ds_read_b32 v54, v40 offset:176
	ds_read_b32 v55, v41 offset:11264
	s_waitcnt lgkmcnt(6)
	v_mfma_f32_32x32x2_f32 v[0:15], v56, v57, v[0:15]
	ds_read_b32 v56, v40 offset:184
	ds_read_b32 v57, v41 offset:11776
	s_waitcnt lgkmcnt(6)
	v_mfma_f32_32x32x2_f32 v[0:15], v50, v51, v[0:15]
	ds_read_b32 v50, v40 offset:192
	ds_read_b32 v51, v41 offset:12288
	s_waitcnt lgkmcnt(6)
	v_mfma_f32_32x32x2_f32 v[0:15], v52, v53, v[0:15]
	ds_read_b32 v52, v40 offset:200
	ds_read_b32 v53, v41 offset:12800
	s_waitcnt lgkmcnt(6)
; DI bf16_t to_bf16(float a) { return (bf16_t)(pk_bf16(a, 0.f) & 0xffffu); }
; DI void pool_item(const Params& p, int layer, int seq, int tile, int g, char* smem) {
;     ...
;     float acc[16];
; #pragma unroll
;     for (int i = 0; i < 16; ++i) acc[i] = 0.f;
; #pragma unroll 1
;     for (int c4 = 0; c4 < 16; ++c4) {
;         const float w0 = sw[(4 * c4) * 64 + e], w1 = sw[(4 * c4 + 1) * 64 + e], w2_ = sw[(4 * c4 + 2) * 64 + e], w3 = sw[(4 * c4 + 3) * 64 + e];
; #pragma unroll
;         for (int i = 0; i < 16; ++i) { const float4 d = *(const float4*)(sd + (tq * 16 + i) * 68 + 4 * c4); acc[i] += d.x * w0 + d.y * w1 + d.z * w2_ + d.w * w3; }
;     }
;     const float ps = p.pool_scale[layer * 256 + g * 64 + e];
; #pragma unroll
;     for (int i = 0; i < 16; ++i) p.H[(rbase + t0 + tq * 16 + i) * DM + 256 + g * 64 + e] = to_bf16(acc[i] * ps);
	v_mfma_f32_32x32x2_f32 v[0:15], v54, v55, v[0:15]
	ds_read_b32 v54, v40 offset:208
	ds_read_b32 v55, v41 offset:13312
	s_waitcnt lgkmcnt(6)
	v_mfma_f32_32x32x2_f32 v[0:15], v56, v57, v[0:15]
	ds_read_b32 v56, v40 offset:216
	ds_read_b32 v57, v41 offset:13824
	s_waitcnt lgkmcnt(6)
	v_mfma_f32_32x32x2_f32 v[0:15], v50, v51, v[0:15]
	ds_read_b32 v50, v40 offset:224
	ds_read_b32 v51, v41 offset:14336
	s_waitcnt lgkmcnt(6)
	v_mfma_f32_32x32x2_f32 v[0:15], v52, v53, v[0:15]
	ds_read_b32 v52, v40 offset:232
	ds_read_b32 v53, v41 offset:14848
	s_waitcnt lgkmcnt(6)
	v_mfma_f32_32x32x2_f32 v[0:15], v54, v55, v[0:15]
	ds_read_b32 v54, v40 offset:240
	ds_read_b32 v55, v41 offset:15360
	s_waitcnt lgkmcnt(6)
	v_mfma_f32_32x32x2_f32 v[0:15], v56, v57, v[0:15]
	ds_read_b32 v56, v40 offset:248
	ds_read_b32 v57, v41 offset:15872
	s_waitcnt lgkmcnt(6)
	v_mfma_f32_32x32x2_f32 v[0:15], v50, v51, v[0:15]
	s_waitcnt lgkmcnt(4)
	v_mfma_f32_32x32x2_f32 v[0:15], v52, v53, v[0:15]
	s_waitcnt lgkmcnt(2)
	v_mfma_f32_32x32x2_f32 v[0:15], v54, v55, v[0:15]
	s_waitcnt lgkmcnt(0)
	v_mfma_f32_32x32x2_f32 v[0:15], v56, v57, v[0:15]
	s_or_b32 s0, s23, s14
	v_or_b32_e32 v44, s0, v44
	v_readlane_b32 s38, v253, 24
	v_readlane_b32 s39, v253, 25
	v_ashrrev_i32_e32 v45, 31, v44
	s_and_b32 s74, s20, 0xffc0
	s_lshl_b32 s0, s23, 1
	s_add_u32 s0, s62, s0
	s_addc_u32 s1, s63, 0
	s_lshl_b32 s4, s74, 11
	s_add_u32 s0, s0, s4
	s_addc_u32 s1, s1, 0
	v_lshl_add_u64 v[44:45], v[44:45], 2, s[38:39]
	global_load_dword v43, v[44:45], off
	v_readlane_b32 s36, v253, 22
	v_readlane_b32 s42, v253, 28
	s_mov_b32 s42, 0x800000
	v_readlane_b32 s37, v253, 23
	v_readlane_b32 s40, v253, 26
	v_readlane_b32 s41, v253, 27
	v_readlane_b32 s43, v253, 29
	v_readlane_b32 s44, v253, 30
	v_readlane_b32 s45, v253, 31
	v_readlane_b32 s46, v253, 32
	v_readlane_b32 s47, v253, 33
	v_readlane_b32 s48, v253, 34
	v_readlane_b32 s49, v253, 35
	v_readlane_b32 s50, v253, 36
	v_readlane_b32 s51, v253, 37
	s_nop 7
	s_waitcnt vmcnt(0)
	v_mul_f32_e32 v46, v0, v43
	v_mul_f32_e32 v47, v1, v43
	v_cvt_pk_bf16_f32 v48, v46, v47
	global_store_short v42, v48, s[0:1] offset:512
	global_store_short_d16_hi v42, v48, s[0:1] offset:2560
	v_mul_f32_e32 v46, v2, v43
	v_mul_f32_e32 v47, v3, v43
	v_cvt_pk_bf16_f32 v48, v46, v47
	v_add_u32_e32 v42, 0x1000, v42
	global_store_short v42, v48, s[0:1] offset:512
	global_store_short_d16_hi v42, v48, s[0:1] offset:2560
	v_mul_f32_e32 v46, v4, v43
	v_mul_f32_e32 v47, v5, v43
	v_cvt_pk_bf16_f32 v48, v46, v47
	v_add_u32_e32 v42, 0x3000, v42
	global_store_short v42, v48, s[0:1] offset:512
	global_store_short_d16_hi v42, v48, s[0:1] offset:2560
	v_mul_f32_e32 v46, v6, v43
	v_mul_f32_e32 v47, v7, v43
	v_cvt_pk_bf16_f32 v48, v46, v47
	v_add_u32_e32 v42, 0x1000, v42
	global_store_short v42, v48, s[0:1] offset:512
	global_store_short_d16_hi v42, v48, s[0:1] offset:2560
	v_mul_f32_e32 v46, v8, v43
	v_mul_f32_e32 v47, v9, v43
	v_cvt_pk_bf16_f32 v48, v46, v47
	v_add_u32_e32 v42, 0x3000, v42
	global_store_short v42, v48, s[0:1] offset:512
	global_store_short_d16_hi v42, v48, s[0:1] offset:2560
	v_mul_f32_e32 v46, v10, v43
	v_mul_f32_e32 v47, v11, v43
	v_cvt_pk_bf16_f32 v48, v46, v47
	v_add_u32_e32 v42, 0x1000, v42
	global_store_short v42, v48, s[0:1] offset:512
	global_store_short_d16_hi v42, v48, s[0:1] offset:2560
	v_mul_f32_e32 v46, v12, v43
	v_mul_f32_e32 v47, v13, v43
	v_cvt_pk_bf16_f32 v48, v46, v47
	v_add_u32_e32 v42, 0x3000, v42
	global_store_short v42, v48, s[0:1] offset:512
	global_store_short_d16_hi v42, v48, s[0:1] offset:2560
	v_mul_f32_e32 v46, v14, v43
	v_mul_f32_e32 v47, v15, v43
	v_cvt_pk_bf16_f32 v48, v46, v47
	v_add_u32_e32 v42, 0x1000, v42
	global_store_short v42, v48, s[0:1] offset:512
	global_store_short_d16_hi v42, v48, s[0:1] offset:2560
	s_barrier
	s_branch .LBB0_242
